# scan o-tile staged via LDS + 16B stores; convert_cache spread over WGs 32..255; attention main-loop iteration A LDS-DMA pieces spread
# speedup vs baseline: 1.0128x; 1.0128x over previous
.LBB0_45:
	s_or_b64 exec, exec, s[6:7]
	s_barrier
	s_load_dword s0, s[94:95], 0xe0
	s_lshl_b32 s19, s2, 3
	s_lshl_b32 s56, s42, 3
	s_mul_i32 s81, s43, s42
	s_cmpk_lt_i32 s2, 0x810
	s_waitcnt lgkmcnt(0)
	s_mul_i32 s81, s81, s0
	s_cselect_b64 s[0:1], -1, 0
	s_ashr_i32 s3, s2, 31
	v_writelane_b32 v252, s0, 0
	s_ashr_i32 s43, s42, 31
	s_and_b32 s6, s42, 7
	v_writelane_b32 v252, s1, 1
	s_lshr_b32 s0, s3, 29
	s_add_i32 s0, s2, s0
	s_ashr_i32 s10, s0, 3
	s_and_b32 s0, s0, -8
	s_sub_i32 s11, s2, s0
	s_and_b32 s0, s2, 7
	s_ashr_i32 s1, s42, 3
	s_mul_i32 s0, s1, s0
	s_lshr_b32 s1, s2, 3
	s_add_i32 s7, s0, s1
	s_cmpk_lg_i32 s42, 0x100
	s_cselect_b64 s[0:1], -1, 0
	s_add_i32 s12, s42, 0x87f
	v_writelane_b32 v252, s0, 2
	s_cmpk_lt_i32 s2, 0x1080
	s_mov_b32 s73, 0
	v_writelane_b32 v252, s1, 3
	s_cselect_b64 s[0:1], -1, 0
	v_writelane_b32 v252, s0, 4
	s_lshr_b32 s13, s2, 7
	v_mov_b32_e32 v173, 0
	v_writelane_b32 v252, s1, 5
	s_and_b32 s0, s2, 0x7f
	s_and_b32 s1, s19, 0xffffe000
	s_lshl_b32 s4, s0, 6
	s_or_b32 s14, s1, s4
	s_cmp_lg_u32 s0, 0
	s_cselect_b64 s[0:1], -1, 0
	s_lshl_b32 s4, s2, 1
	s_and_b32 s4, s4, 0x7ffffff0
	s_add_i32 s15, s4, 0x6000
	s_cmpk_lt_i32 s2, 0xa0
	s_cselect_b64 s[4:5], -1, 0
	s_cmpk_lt_i32 s42, 0xc0
	v_writelane_b32 v252, s4, 6
	s_cselect_b64 s[8:9], -1, 0
	s_add_i32 s72, s2, 0xffffffe0
	v_writelane_b32 v252, s5, 7
	v_writelane_b32 v252, s8, 8
	s_or_b64 s[4:5], s[4:5], s[8:9]
	s_movk_i32 s33, 0xc0
	v_writelane_b32 v252, s9, 9
	v_writelane_b32 v252, s4, 10
	s_lshl_b64 s[8:9], s[72:73], 9
	s_mul_hi_i32 s85, s42, 0x16000
	v_writelane_b32 v252, s5, 11
	s_lshl_b64 s[4:5], s[2:3], 9
	v_writelane_b32 v252, s4, 12
	s_mul_i32 s84, s42, 0x16000
	s_movk_i32 s87, 0x4040
	v_writelane_b32 v252, s5, 13
	s_lshl_b64 s[4:5], s[42:43], 9
	v_writelane_b32 v252, s4, 14
	s_movk_i32 s92, 0x7fff
	s_movk_i32 s72, 0x300
	v_writelane_b32 v252, s5, 15
	s_add_i32 s4, s42, 0xffffffe0
	v_writelane_b32 v252, s8, 16
	s_mov_b32 s5, s73
	s_lshl_b64 s[4:5], s[4:5], 9
	v_writelane_b32 v252, s9, 17
	v_writelane_b32 v252, s4, 18
	s_cmpk_lt_i32 s2, 0x204
	v_mov_b32_e32 v216, 0x358637bd
	v_writelane_b32 v252, s5, 19
	s_cselect_b64 s[4:5], -1, 0
	v_writelane_b32 v252, s4, 20
	s_movk_i32 s86, 0x3000
	v_mov_b32_e32 v217, 0x1000
	v_writelane_b32 v252, s5, 21
	s_lshl_b32 s4, s11, 6
	s_or_b32 s4, s4, 4
	s_cmp_lt_i32 s11, 0
	s_movk_i32 s5, 0x103
	s_cselect_b32 s5, s5, 0x102
	s_mul_i32 s5, s11, s5
	s_add_i32 s5, s5, s10
	s_ashr_i32 s8, s5, 31
	s_lshr_b32 s8, s8, 25
	s_add_i32 s8, s5, s8
	s_ashr_i32 s9, s8, 7
	s_lshl_b32 s16, s9, 3
	s_sub_i32 s9, 0x81, s16
	s_and_b32 s8, s8, 0xffffff80
	s_min_u32 s17, s9, 8
	s_sub_i32 s18, s5, s8
	s_cmp_eq_u32 s6, 0
	s_cselect_b32 s6, s7, s2
	s_cmpk_lt_i32 s6, 0x80
	s_cselect_b64 s[8:9], -1, 0
	v_writelane_b32 v252, s8, 22
	s_add_i32 s7, s6, 0x800
	v_cvt_f32_ubyte0_e32 v1, s17
	v_writelane_b32 v252, s9, 23
	v_writelane_b32 v252, s7, 24
	s_and_b32 s7, s6, 31
	v_writelane_b32 v252, s6, 25
	s_ashr_i32 s6, s6, 3
	s_and_b32 s6, s6, -4
	v_writelane_b32 v252, s6, 26
	s_xor_b32 s6, s7, 63
	v_writelane_b32 v252, s7, 27
	s_cmpk_lt_i32 s2, 0x1000
	v_writelane_b32 v252, s6, 28
	s_cselect_b64 s[6:7], -1, 0
	s_and_b64 s[8:9], s[6:7], exec
	s_cselect_b32 s8, 64, 16
	v_writelane_b32 v252, s8, 29
	s_cselect_b32 s8, s14, s15
	v_writelane_b32 v252, s8, 30
	s_cselect_b32 s8, s13, s2
	s_lshl_b32 s8, s8, 7
	s_and_b32 s8, s8, 0x380
	s_cmp_lt_i32 s11, 4
	s_mulk_i32 s11, 0x41
	s_cselect_b32 s4, s11, s4
	v_cvt_f32_i32_e32 v0, s18
	v_rcp_iflag_f32_e32 v2, v1
	s_add_i32 s4, s4, s10
	v_writelane_b32 v252, s8, 31
	s_ashr_i32 s8, s4, 31
	s_lshr_b32 s8, s8, 27
	s_add_i32 s8, s4, s8
	v_mul_f32_e32 v2, v0, v2
	s_ashr_i32 s9, s8, 5
	s_and_b64 s[0:1], s[0:1], s[6:7]
	v_trunc_f32_e32 v2, v2
	s_lshl_b32 s9, s9, 3
	v_writelane_b32 v252, s0, 32
	v_fma_f32 v0, -v2, v1, v0
	v_cvt_i32_f32_e32 v2, v2
	s_sub_i32 s10, 0x81, s9
	s_andn2_b32 s8, s8, 31
	v_writelane_b32 v252, s1, 33
	s_ashr_i32 s0, s18, 30
	s_min_u32 s10, s10, 8
	s_sub_i32 s4, s4, s8
	s_or_b32 s6, s0, 1
	v_cmp_ge_f32_e64 s[0:1], |v0|, v1
	s_and_b64 s[0:1], s[0:1], exec
	s_cselect_b32 s0, s6, 0
	v_readfirstlane_b32 s1, v2
	s_add_i32 s0, s1, s0
	s_abs_i32 s1, s42
	v_cvt_f32_u32_e32 v0, s1
	s_sub_i32 s7, 0, s1
	s_sext_i32_i8 s6, s0
	s_mul_i32 s0, s0, s17
	v_rcp_iflag_f32_e32 v0, v0
	v_writelane_b32 v252, s6, 34
	s_sub_i32 s0, s18, s0
	s_abs_i32 s6, s12
	v_mul_f32_e32 v0, 0x4f7ffffe, v0
	v_cvt_u32_f32_e32 v0, v0
	s_sext_i32_i8 s0, s0
	s_add_i32 s0, s16, s0
	v_writelane_b32 v252, s0, 35
	v_readfirstlane_b32 s8, v0
	s_mul_i32 s7, s7, s8
	s_mul_hi_u32 s7, s8, s7
	s_add_i32 s8, s8, s7
	s_mul_hi_u32 s7, s6, s8
	s_mul_i32 s8, s7, s1
	s_xor_b32 s0, s12, s42
	s_sub_i32 s6, s6, s8
	s_ashr_i32 s0, s0, 31
	s_add_i32 s8, s7, 1
	s_sub_i32 s11, s6, s1
	v_cvt_f32_ubyte0_e32 v1, s10
	s_cmp_ge_u32 s6, s1
	v_cvt_f32_i32_e32 v0, s4
	v_rcp_iflag_f32_e32 v2, v1
	s_cselect_b32 s7, s8, s7
	s_cselect_b32 s6, s11, s6
	s_add_i32 s8, s7, 1
	s_cmp_ge_u32 s6, s1
	s_cselect_b32 s1, s8, s7
	v_mul_f32_e32 v2, v0, v2
	s_xor_b32 s1, s1, s0
	v_trunc_f32_e32 v2, v2
	s_sub_i32 s0, s1, s0
	v_fma_f32 v0, -v2, v1, v0
	v_cvt_i32_f32_e32 v2, v2
	v_writelane_b32 v252, s0, 36
	s_ashr_i32 s0, s4, 30
	s_or_b32 s6, s0, 1
	v_cmp_ge_f32_e64 s[0:1], |v0|, v1
	s_and_b64 s[0:1], s[0:1], exec
	s_cselect_b32 s0, s6, 0
	v_readfirstlane_b32 s1, v2
	s_add_i32 s0, s1, s0
	s_sext_i32_i8 s1, s0
	v_writelane_b32 v252, s1, 37
	s_mul_i32 s1, s0, s10
	s_sub_i32 s1, s4, s1
	s_sext_i32_i8 s1, s1
	s_add_i32 s6, s9, s1
	s_movk_i32 s5, 0x80
	s_mov_b32 s4, s6
	s_ashr_i32 s7, s6, 31
	v_writelane_b32 v252, s4, 38
	s_lshl_b64 s[6:7], s[6:7], 19
	s_bfe_i64 s[0:1], s[0:1], 0x80000
	v_writelane_b32 v252, s5, 39
	v_writelane_b32 v252, s6, 40
	s_lshl_b64 s[0:1], s[0:1], 19
	s_ashr_i32 s57, s56, 31
	v_writelane_b32 v252, s7, 41
	v_writelane_b32 v252, s0, 42
	s_lshl_b64 s[60:61], s[56:57], 11
	v_mbcnt_lo_u32_b32 v0, -1, 0
	v_writelane_b32 v252, s1, 43
	s_lshl_b64 s[0:1], s[56:57], 12
	v_writelane_b32 v252, s0, 44
	v_mov_b32_e32 v218, 0x2000
	v_mov_b32_e32 v219, 0x2cfc000
	v_writelane_b32 v252, s1, 45
	v_writelane_b32 v252, s19, 46
	s_add_i32 s0, s19, s56
	v_writelane_b32 v252, s0, 47
	s_add_i32 s0, s2, s42
	s_lshl_b32 s1, s0, 3
	v_writelane_b32 v252, s1, 48
	s_lshl_b32 s0, s0, 1
	v_writelane_b32 v252, s0, 49
	s_lshl_b32 s0, s42, 1
	v_writelane_b32 v252, s0, 50
	s_lshl_b64 s[0:1], s[2:3], 2
	s_add_u32 s0, s0, 0x2cf5000
	s_addc_u32 s1, s1, 0
	v_writelane_b32 v252, s0, 51
	s_lshl_b64 s[6:7], s[42:43], 2
	v_mov_b32_e32 v220, 1
	v_writelane_b32 v252, s1, 52
	s_mul_hi_i32 s1, s2, 0x16000
	s_mul_i32 s0, s2, 0x16000
	v_writelane_b32 v252, s0, 53
	v_mov_b32_e32 v221, 0x3f4ccccd
	v_mbcnt_hi_u32_b32 v215, -1, v0
	v_writelane_b32 v252, s1, 54
	s_add_i32 s0, 0, 0x20000
	v_writelane_b32 v252, s0, 55
	s_add_i32 s0, 0, 0x20004
	v_writelane_b32 v252, s0, 56
	s_add_i32 s0, 0, 0x4400
	v_writelane_b32 v252, s0, 57
	s_add_i32 s0, 0, 0xd000
	v_writelane_b32 v252, s0, 58
	v_writelane_b32 v252, s6, 59
	v_mov_b64_e32 v[174:175], 0x80f
	v_mov_b64_e32 v[176:177], 0x810
	v_writelane_b32 v252, s7, 60
	s_lshl_b64 s[6:7], s[56:57], 13
	v_writelane_b32 v252, s6, 61
	v_mov_b32_e32 v222, 0xffffe003
	v_mov_b32_e32 v223, 0x7f800000
	v_writelane_b32 v252, s7, 62
	v_writelane_b32 v252, s94, 63
	v_mov_b32_e32 v224, 0xff800000
	v_mov_b32_e32 v225, 0x41b17218
	v_writelane_b32 v251, s95, 0
	v_mov_b32_e32 v226, 0x3fb8aa3b
	v_mov_b32_e32 v227, 0xffffff00
	v_mov_b32_e32 v228, 0xffffff80
	v_mov_b32_e32 v246, v173
	v_mov_b32_e32 v247, v173
	v_mov_b32_e32 v248, v173
	v_mov_b32_e32 v249, v173
	v_mov_b64_e32 v[178:179], 0x203
	v_mov_b64_e32 v[180:181], 0x204
	s_movk_i32 s4, 0x60
	s_add_i32 s1, 0, 0x11800
	s_add_i32 s0, 0, 0x17d00
	s_movk_i32 s69, 0xf0
	s_movk_i32 s93, 0x70
	s_mov_b64 s[76:77], 0
	s_mov_b64 s[78:79], 0x80
	s_mov_b32 s80, 0x3e38aa3b
	v_writelane_b32 v251, s96, 1
	s_nop 1
	v_writelane_b32 v251, s97, 2
	s_branch .LBB0_48

.LBB0_509:
	v_mov_b32_e32 v96, v206
	s_waitcnt vmcnt(0)
	s_barrier
	v_lshl_add_u64 v[162:163], v[198:199], 0, s[10:11]
	v_lshl_add_u64 v[160:161], v[200:201], 0, s[10:11]
	v_lshl_add_u64 v[158:159], v[202:203], 0, s[10:11]
	v_lshl_add_u64 v[156:157], v[204:205], 0, s[10:11]
	s_add_i32 s58, s88, 0xffff8000
	s_and_b32 s58, s58, 0x10000
	s_add_i32 s74, s47, s58
	s_mov_b64 s[100:101], 0x10000
	s_mov_b32 m0, s74
	v_lshl_add_u64 v[254:255], v[162:163], 0, s[100:101]
	global_load_lds_dwordx4 v[254:255], off
.LBB0_511:
	v_ashrrev_i32_e32 v97, 5, v96
	v_lshlrev_b32_e32 v98, 8, v96
	v_add_u32_e32 v99, s49, v97
	v_bfe_u32 v120, v96, 2, 2
	v_and_b32_e32 v98, 0x1f00, v98
	v_bitop3_b32 v99, v99, v96, 15 bitop3:0x78
	s_add_i32 s58, s88, 0xfffe8000
	v_lshlrev_b32_e32 v100, 4, v99
	v_lshlrev_b32_e32 v121, 10, v97
	v_lshlrev_b32_e32 v122, 8, v120
	v_lshrrev_b32_e32 v97, 3, v96
	v_bfe_u32 v99, v96, 1, 1
	s_and_b32 s75, s58, 0x10000
	v_and_or_b32 v97, v97, 2, v99
	v_lshlrev_b32_e32 v96, 3, v96
	s_add_i32 s74, s75, 0
	v_lshlrev_b32_e32 v123, 4, v97
	v_and_b32_e32 v124, 8, v96
	v_add_u32_e32 v101, s74, v98
	v_add_u32_e32 v166, v101, v100
	ds_read_b128 v[96:99], v166 offset:32768
	v_xad_u32 v165, v100, 32, v101
	ds_read_b128 v[116:119], v165 offset:32768
	v_xad_u32 v164, v100, 64, v101
	v_xad_u32 v127, v100, s4, v101
	s_waitcnt lgkmcnt(1)
	v_mfma_f32_32x32x16_bf16 v[96:111], v[96:99], v[112:115], 0
	s_and_b32 s90, s88, 0x18000
	s_add_i32 s58, s90, 0
	v_add3_u32 v121, s58, v121, v122
	v_add3_u32 v124, v121, v123, v124
	v_lshlrev_b32_e32 v125, 6, v120
	v_add_u32_e32 v126, v124, v125
	v_xad_u32 v167, v125, 64, v124
	s_waitcnt lgkmcnt(0)
	v_mfma_f32_32x32x16_bf16 v[96:111], v[116:119], v[136:139], v[96:111]
	ds_read_b128 v[116:119], v164 offset:32768
	ds_read_b128 v[120:123], v127 offset:32768
	v_xad_u32 v238, v125, s5, v124
	v_xad_u32 v239, v125, s33, v124
	v_max_f32_e32 v124, v65, v65
	v_max_f32_e32 v125, v64, v64
	v_max_f32_e32 v124, v125, v124
	s_waitcnt lgkmcnt(1)
	v_mfma_f32_32x32x16_bf16 v[96:111], v[116:119], v[132:135], v[96:111]
	v_max3_f32 v124, v124, v66, v67
	ds_read_b64_tr_b16 v[116:117], v126 offset:16384
	ds_read_b64_tr_b16 v[118:119], v126 offset:18432
	v_max3_f32 v124, v124, v68, v69
	v_max3_f32 v124, v124, v70, v71
	v_max3_f32 v124, v124, v72, v73
	v_max3_f32 v124, v124, v74, v75
	s_waitcnt lgkmcnt(2)
	v_mfma_f32_32x32x16_bf16 v[96:111], v[120:123], v[128:131], v[96:111]
	v_max3_f32 v124, v124, v76, v77
	v_max3_f32 v124, v124, v78, v79
	v_max3_f32 v124, v124, v80, v81
	v_max3_f32 v124, v124, v82, v83
	v_max3_f32 v124, v124, v84, v85
	ds_read_b64_tr_b16 v[120:121], v126 offset:20480
	ds_read_b64_tr_b16 v[122:123], v126 offset:22528
	s_waitcnt lgkmcnt(2)
	v_mfma_f32_32x32x16_bf16 v[48:63], v[116:119], v[140:143], v[48:63]
	v_max3_f32 v116, v124, v86, v87
	v_max3_f32 v116, v116, v88, v89
	v_max3_f32 v116, v116, v90, v91
	v_max3_f32 v116, v116, v92, v93
	v_max3_f32 v124, v116, v94, v95
	ds_bpermute_b32 v125, v191, v124
	ds_read_b64_tr_b16 v[116:117], v126 offset:24576
	ds_read_b64_tr_b16 v[118:119], v126 offset:26624
	s_waitcnt lgkmcnt(3)
	v_mfma_f32_32x32x16_bf16 v[48:63], v[120:123], v[148:151], v[48:63]
	v_lshl_add_u64 v[254:255], v[160:161], 0, s[100:101]
	global_load_lds_dwordx4 v[254:255], off offset:1024
	ds_read_b64_tr_b16 v[120:121], v126 offset:28672
	s_waitcnt lgkmcnt(3)
	v_max3_f32 v197, v193, v124, v125
	v_sub_f32_e32 v64, v64, v197
	v_exp_f32_e32 v244, v64
	v_sub_f32_e32 v64, v80, v197
	v_exp_f32_e32 v245, v64
	ds_read_b64_tr_b16 v[122:123], v126 offset:30720
	v_sub_f32_e32 v64, v65, v197
	v_exp_f32_e32 v124, v64
	v_add_f32_e32 v125, v244, v245
	s_waitcnt lgkmcnt(2)
	v_mfma_f32_32x32x16_bf16 v[48:63], v[116:119], v[144:147], v[48:63]
	v_sub_f32_e32 v64, v81, v197
	v_exp_f32_e32 v172, v64
	ds_read_b64_tr_b16 v[116:117], v167 offset:16384
	ds_read_b64_tr_b16 v[118:119], v167 offset:18432
	v_pk_add_f32 v[64:65], v[124:125], v[172:173]
	s_nop 0
	v_pk_add_f32 v[168:169], v[64:65], v[64:65] op_sel_hi:[0,1]
	v_sub_f32_e32 v64, v66, v197
	v_sub_f32_e32 v65, v82, v197
	s_waitcnt lgkmcnt(2)
	v_mfma_f32_32x32x16_bf16 v[48:63], v[120:123], v[152:155], v[48:63]
	v_exp_f32_e32 v125, v64
	v_sub_f32_e32 v64, v67, v197
	v_exp_f32_e32 v126, v65
	v_exp_f32_e32 v120, v64
	v_sub_f32_e32 v64, v83, v197
	v_exp_f32_e32 v168, v64
	v_add_f32_e32 v121, v125, v126
	ds_read_b64_tr_b16 v[64:65], v167 offset:20480
	ds_read_b64_tr_b16 v[66:67], v167 offset:22528
	v_pk_add_f32 v[80:81], v[120:121], v[168:169]
	ds_read_b64_tr_b16 v[82:83], v167 offset:26624
	v_pk_add_f32 v[170:171], v[80:81], v[80:81] op_sel_hi:[0,1]
	s_waitcnt lgkmcnt(3)
	v_mfma_f32_32x32x16_bf16 v[32:47], v[116:119], v[140:143], v[32:47]
	v_sub_f32_e32 v68, v68, v197
	v_exp_f32_e32 v121, v68
	v_sub_f32_e32 v68, v84, v197
	v_exp_f32_e32 v169, v68
	ds_read_b64_tr_b16 v[80:81], v167 offset:24576
	v_sub_f32_e32 v68, v69, v197
	v_sub_f32_e32 v69, v85, v197
	v_add_f32_e32 v123, v121, v169
	s_waitcnt lgkmcnt(2)
	v_mfma_f32_32x32x16_bf16 v[32:47], v[64:67], v[148:151], v[32:47]
	v_sub_f32_e32 v64, v70, v197
	v_exp_f32_e32 v122, v68
	v_exp_f32_e32 v170, v69
	v_exp_f32_e32 v250, v64
	v_sub_f32_e32 v64, v86, v197
	v_exp_f32_e32 v65, v64
	ds_read_b64_tr_b16 v[116:117], v167 offset:28672
	ds_read_b64_tr_b16 v[118:119], v167 offset:30720
	v_pk_add_f32 v[66:67], v[122:123], v[170:171]
	v_add_f32_e32 v241, v250, v65
	v_pk_add_f32 v[66:67], v[66:67], v[66:67] op_sel_hi:[0,1]
	s_waitcnt lgkmcnt(2)
	v_mfma_f32_32x32x16_bf16 v[32:47], v[80:83], v[144:147], v[32:47]
	v_sub_f32_e32 v64, v71, v197
	v_exp_f32_e32 v240, v64
	v_sub_f32_e32 v64, v87, v197
	v_exp_f32_e32 v66, v64
	ds_read_b64_tr_b16 v[80:81], v238 offset:16384
	ds_read_b64_tr_b16 v[82:83], v238 offset:18432
	v_sub_f32_e32 v64, v72, v197
	v_pk_add_f32 v[68:69], v[240:241], v[66:67]
	v_exp_f32_e32 v123, v64
	v_pk_add_f32 v[68:69], v[68:69], v[68:69] op_sel_hi:[0,1]
	s_waitcnt lgkmcnt(2)
	v_mfma_f32_32x32x16_bf16 v[32:47], v[116:119], v[152:155], v[32:47]
	v_lshl_add_u64 v[254:255], v[158:159], 0, s[100:101]
	global_load_lds_dwordx4 v[254:255], off offset:2048
	v_sub_f32_e32 v64, v88, v197
	v_exp_f32_e32 v67, v64
	v_sub_f32_e32 v64, v73, v197
	v_exp_f32_e32 v88, v64
	v_sub_f32_e32 v64, v89, v197
	v_exp_f32_e32 v68, v64
	ds_read_b64_tr_b16 v[84:85], v238 offset:20480
	ds_read_b64_tr_b16 v[86:87], v238 offset:22528
	v_add_f32_e32 v89, v123, v67
	v_pk_add_f32 v[70:71], v[88:89], v[68:69]
	s_waitcnt lgkmcnt(2)
	v_mfma_f32_32x32x16_bf16 v[16:31], v[80:83], v[140:143], v[16:31]
	v_sub_f32_e32 v64, v74, v197
	v_exp_f32_e32 v89, v64
	v_sub_f32_e32 v64, v90, v197
	v_exp_f32_e32 v69, v64
	ds_read_b64_tr_b16 v[80:81], v238 offset:24576
	ds_read_b64_tr_b16 v[82:83], v238 offset:26624
	v_pk_add_f32 v[70:71], v[70:71], v[70:71] op_sel_hi:[0,1]
	v_add_f32_e32 v243, v89, v69
	v_sub_f32_e32 v64, v75, v197
	s_waitcnt lgkmcnt(2)
	v_mfma_f32_32x32x16_bf16 v[16:31], v[84:87], v[148:151], v[16:31]
	v_exp_f32_e32 v242, v64
	v_sub_f32_e32 v64, v91, v197
	v_exp_f32_e32 v70, v64
	ds_read_b64_tr_b16 v[84:85], v238 offset:28672
	ds_read_b64_tr_b16 v[86:87], v238 offset:30720
	v_sub_f32_e32 v64, v76, v197
	v_pk_add_f32 v[72:73], v[242:243], v[70:71]
	v_sub_f32_e32 v71, v92, v197
	v_pk_add_f32 v[72:73], v[72:73], v[72:73] op_sel_hi:[0,1]
	s_waitcnt lgkmcnt(2)
	v_mfma_f32_32x32x16_bf16 v[16:31], v[80:83], v[144:147], v[16:31]
	v_exp_f32_e32 v167, v64
	v_sub_f32_e32 v64, v77, v197
	v_exp_f32_e32 v71, v71
	v_exp_f32_e32 v90, v64
	v_sub_f32_e32 v64, v93, v197
	v_exp_f32_e32 v72, v64
	ds_read_b64_tr_b16 v[80:81], v239 offset:16384
	ds_read_b64_tr_b16 v[82:83], v239 offset:18432
	v_add_f32_e32 v91, v167, v71
	v_pk_add_f32 v[74:75], v[90:91], v[72:73]
	ds_read_b64_tr_b16 v[76:77], v239 offset:24576
	v_pk_add_f32 v[74:75], v[74:75], v[74:75] op_sel_hi:[0,1]
	s_waitcnt lgkmcnt(3)
	v_mfma_f32_32x32x16_bf16 v[16:31], v[84:87], v[152:155], v[16:31]
	v_sub_f32_e32 v64, v78, v197
	v_exp_f32_e32 v91, v64
	v_sub_f32_e32 v64, v94, v197
	v_exp_f32_e32 v73, v64
	ds_read_b64_tr_b16 v[84:85], v239 offset:20480
	ds_read_b64_tr_b16 v[86:87], v239 offset:22528
	v_sub_f32_e32 v64, v79, v197
	v_add_f32_e32 v93, v91, v73
	v_sub_f32_e32 v74, v95, v197
	s_waitcnt lgkmcnt(3)
	v_mfma_f32_32x32x16_bf16 v[0:15], v[80:83], v[140:143], v[0:15]
	v_exp_f32_e32 v92, v64
	v_exp_f32_e32 v74, v74
	ds_read_b64_tr_b16 v[80:81], v239 offset:28672
	ds_read_b64_tr_b16 v[82:83], v239 offset:30720
	v_pk_add_f32 v[78:79], v[92:93], v[74:75]
	s_nop 0
	v_add_f32_e32 v238, v78, v79
	ds_read_b64_tr_b16 v[78:79], v239 offset:26624
	s_waitcnt lgkmcnt(3)
	v_mfma_f32_32x32x16_bf16 v[0:15], v[84:87], v[148:151], v[0:15]
	v_lshl_add_u64 v[254:255], v[156:157], 0, s[100:101]
	global_load_lds_dwordx4 v[254:255], off offset:3072
	v_cvt_pk_bf16_f32 v117, v125, v120
	v_cvt_pk_bf16_f32 v118, v121, v122
	v_cvt_pk_bf16_f32 v120, v123, v88
	v_cvt_pk_bf16_f32 v121, v89, v242
	s_waitcnt lgkmcnt(0)
	v_mfma_f32_32x32x16_bf16 v[0:15], v[76:79], v[144:147], v[0:15]
	ds_read_b128 v[76:79], v166 offset:40960
	v_cvt_pk_bf16_f32 v122, v167, v90
	v_cvt_pk_bf16_f32 v123, v91, v92
	v_mfma_f32_32x32x16_bf16 v[0:15], v[80:83], v[152:155], v[0:15]
	s_waitcnt lgkmcnt(0)
	v_mfma_f32_32x32x16_bf16 v[80:95], v[76:79], v[112:115], 0
	ds_read_b128 v[76:79], v165 offset:40960
	s_waitcnt lgkmcnt(0)
	v_mfma_f32_32x32x16_bf16 v[80:95], v[76:79], v[136:139], v[80:95]
	ds_read_b128 v[76:79], v164 offset:40960
	s_waitcnt lgkmcnt(0)
	v_mfma_f32_32x32x16_bf16 v[80:95], v[76:79], v[132:135], v[80:95]
	ds_read_b128 v[76:79], v127 offset:40960
	v_sub_f32_e32 v64, v193, v197
	v_exp_f32_e32 v64, v64
	v_cvt_pk_bf16_f32 v116, v244, v124
	v_fmac_f32_e32 v238, v195, v64
	s_waitcnt lgkmcnt(0)
	v_mfma_f32_32x32x16_bf16 v[80:95], v[76:79], v[128:131], v[80:95]
	v_cvt_pk_bf16_f32 v119, v250, v240
	v_cvt_pk_bf16_f32 v124, v245, v172
	v_cvt_pk_bf16_f32 v125, v126, v168
	v_cvt_pk_bf16_f32 v126, v169, v170
	v_cvt_pk_bf16_f32 v127, v65, v66
	v_cvt_pk_bf16_f32 v140, v67, v68
	v_cvt_pk_bf16_f32 v141, v69, v70
	v_cvt_pk_bf16_f32 v142, v71, v72
	v_cvt_pk_bf16_f32 v143, v73, v74
	v_cmp_neq_f32_e32 vcc, 1.0, v64
	s_cbranch_vccz .LBB0_513
	v_pk_mul_f32 v[62:63], v[62:63], v[64:65] op_sel_hi:[1,0]
	v_pk_mul_f32 v[60:61], v[60:61], v[64:65] op_sel_hi:[1,0]
	v_pk_mul_f32 v[58:59], v[58:59], v[64:65] op_sel_hi:[1,0]
	v_pk_mul_f32 v[56:57], v[56:57], v[64:65] op_sel_hi:[1,0]
	v_pk_mul_f32 v[54:55], v[54:55], v[64:65] op_sel_hi:[1,0]
	v_pk_mul_f32 v[52:53], v[52:53], v[64:65] op_sel_hi:[1,0]
	v_pk_mul_f32 v[50:51], v[50:51], v[64:65] op_sel_hi:[1,0]
	v_pk_mul_f32 v[48:49], v[48:49], v[64:65] op_sel_hi:[1,0]
	v_pk_mul_f32 v[46:47], v[46:47], v[64:65] op_sel_hi:[1,0]
	v_pk_mul_f32 v[44:45], v[44:45], v[64:65] op_sel_hi:[1,0]
	v_pk_mul_f32 v[42:43], v[42:43], v[64:65] op_sel_hi:[1,0]
	v_pk_mul_f32 v[40:41], v[40:41], v[64:65] op_sel_hi:[1,0]
	v_pk_mul_f32 v[38:39], v[38:39], v[64:65] op_sel_hi:[1,0]
	v_pk_mul_f32 v[36:37], v[36:37], v[64:65] op_sel_hi:[1,0]
	v_pk_mul_f32 v[34:35], v[34:35], v[64:65] op_sel_hi:[1,0]
	v_pk_mul_f32 v[32:33], v[32:33], v[64:65] op_sel_hi:[1,0]
	v_pk_mul_f32 v[30:31], v[30:31], v[64:65] op_sel_hi:[1,0]
	v_pk_mul_f32 v[28:29], v[28:29], v[64:65] op_sel_hi:[1,0]
	v_pk_mul_f32 v[26:27], v[26:27], v[64:65] op_sel_hi:[1,0]
	v_pk_mul_f32 v[24:25], v[24:25], v[64:65] op_sel_hi:[1,0]
	v_pk_mul_f32 v[22:23], v[22:23], v[64:65] op_sel_hi:[1,0]
	v_pk_mul_f32 v[20:21], v[20:21], v[64:65] op_sel_hi:[1,0]
	v_pk_mul_f32 v[18:19], v[18:19], v[64:65] op_sel_hi:[1,0]
	v_pk_mul_f32 v[16:17], v[16:17], v[64:65] op_sel_hi:[1,0]
	v_pk_mul_f32 v[14:15], v[14:15], v[64:65] op_sel_hi:[1,0]
	v_pk_mul_f32 v[12:13], v[12:13], v[64:65] op_sel_hi:[1,0]
	v_pk_mul_f32 v[10:11], v[10:11], v[64:65] op_sel_hi:[1,0]
	v_pk_mul_f32 v[8:9], v[8:9], v[64:65] op_sel_hi:[1,0]
	v_pk_mul_f32 v[6:7], v[6:7], v[64:65] op_sel_hi:[1,0]
	v_pk_mul_f32 v[4:5], v[4:5], v[64:65] op_sel_hi:[1,0]
	v_pk_mul_f32 v[2:3], v[2:3], v[64:65] op_sel_hi:[1,0]
	v_pk_mul_f32 v[0:1], v[0:1], v[64:65] op_sel_hi:[1,0]

.LBB0_1092:
	v_lshlrev_b32_e32 v146, 16, v32
	v_and_b32_e32 v147, 0xffff0000, v32
	v_lshlrev_b32_e32 v148, 16, v33
	v_and_b32_e32 v149, 0xffff0000, v33
	v_xor_b32_e32 v32, 0x80000000, v1
	v_xor_b32_e32 v33, 0x80000000, v0
	v_cvt_pk_bf16_f32 v150, v33, v32
	v_xor_b32_e32 v32, 0x80000000, v2
	v_xor_b32_e32 v33, 0x80000000, v3
	v_cvt_pk_bf16_f32 v151, v32, v33
	v_xor_b32_e32 v32, 0x80000000, v4
	v_xor_b32_e32 v33, 0x80000000, v5
	v_cvt_pk_bf16_f32 v152, v32, v33
	v_xor_b32_e32 v32, 0x80000000, v6
	v_xor_b32_e32 v33, 0x80000000, v7
	v_cvt_pk_bf16_f32 v153, v32, v33
	v_xor_b32_e32 v32, 0x80000000, v8
	v_xor_b32_e32 v33, 0x80000000, v9
	v_cvt_pk_bf16_f32 v154, v32, v33
	v_xor_b32_e32 v32, 0x80000000, v10
	v_xor_b32_e32 v33, 0x80000000, v11
	v_cvt_pk_bf16_f32 v155, v32, v33
	v_xor_b32_e32 v32, 0x80000000, v12
	v_xor_b32_e32 v33, 0x80000000, v13
	v_cvt_pk_bf16_f32 v156, v32, v33
	v_xor_b32_e32 v32, 0x80000000, v14
	v_xor_b32_e32 v33, 0x80000000, v15
	v_cvt_pk_bf16_f32 v157, v32, v33
	v_xor_b32_e32 v32, 0x80000000, v16
	v_xor_b32_e32 v33, 0x80000000, v17
	v_cvt_pk_bf16_f32 v158, v32, v33
	v_xor_b32_e32 v32, 0x80000000, v18
	v_xor_b32_e32 v33, 0x80000000, v19
	v_cvt_pk_bf16_f32 v159, v32, v33
	v_xor_b32_e32 v32, 0x80000000, v20
	v_xor_b32_e32 v33, 0x80000000, v21
	v_cvt_pk_bf16_f32 v160, v32, v33
	v_xor_b32_e32 v32, 0x80000000, v22
	v_xor_b32_e32 v33, 0x80000000, v23
	v_cvt_pk_bf16_f32 v161, v32, v33
	v_xor_b32_e32 v32, 0x80000000, v28
	v_xor_b32_e32 v33, 0x80000000, v29
	s_bitcmp1_b32 s19, 0
	v_cvt_pk_bf16_f32 v162, v32, v33
	v_xor_b32_e32 v32, 0x80000000, v30
	v_xor_b32_e32 v33, 0x80000000, v31
	s_cselect_b32 s19, 0xe000, 0
	v_cvt_pk_bf16_f32 v163, v32, v33
	v_xor_b32_e32 v32, 0x80000000, v24
	v_xor_b32_e32 v33, 0x80000000, v25
	s_add_i32 s19, s19, 0
	v_cvt_pk_bf16_f32 v164, v32, v33
	v_xor_b32_e32 v32, 0x80000000, v26
	v_xor_b32_e32 v33, 0x80000000, v27
	v_and_b32_e32 v43, -16, v40
	v_cvt_pk_bf16_f32 v165, v32, v33
	v_lshlrev_b32_e32 v32, 4, v135
	v_lshl_add_u32 v33, v135, 8, s19
	v_add_u32_e32 v170, 64, v43
	v_add_u32_e32 v172, 0x80, v43
	v_add_u32_e32 v186, 0xc0, v43
	v_xad_u32 v137, v32, v43, v33
	v_xad_u32 v171, v170, v32, v33
	v_xad_u32 v172, v172, v32, v33
	v_xad_u32 v210, v186, v32, v33
	v_lshlrev_b32_e32 v138, 16, v38
	v_and_b32_e32 v139, 0xffff0000, v38
	v_lshlrev_b32_e32 v140, 16, v39
	v_and_b32_e32 v141, 0xffff0000, v39
	v_lshlrev_b32_e32 v42, 3, v40
	ds_read_b128 v[38:41], v137
	ds_read_b128 v[166:169], v171
	ds_read_b128 v[182:185], v172
	ds_read_b128 v[186:189], v210
	ds_read_b128 v[190:193], v137 offset:4096
	ds_read_b128 v[194:197], v171 offset:4096
	ds_read_b128 v[198:201], v172 offset:4096
	ds_read_b128 v[202:205], v210 offset:4096
	v_lshlrev_b32_e32 v142, 16, v34
	v_and_b32_e32 v143, 0xffff0000, v34
	v_lshlrev_b32_e32 v144, 16, v35
	v_and_b32_e32 v145, 0xffff0000, v35
	v_lshlrev_b32_e32 v34, 16, v36
	v_and_b32_e32 v35, 0xffff0000, v36
	v_lshlrev_b32_e32 v36, 16, v37
	v_and_b32_e32 v37, 0xffff0000, v37
	s_waitcnt lgkmcnt(7)
	v_mfma_f32_16x16x32_bf16 v[38:41], v[38:41], v[150:153], v[138:141]
	s_waitcnt lgkmcnt(6)
	v_mfma_f32_16x16x32_bf16 v[38:41], v[166:169], v[154:157], v[38:41]
	s_waitcnt lgkmcnt(5)
	v_mfma_f32_16x16x32_bf16 v[38:41], v[182:185], v[158:161], v[38:41]
	s_waitcnt lgkmcnt(4)
	v_mfma_f32_16x16x32_bf16 v[38:41], v[186:189], v[162:165], v[38:41]
	ds_read_b128 v[138:141], v137 offset:8192
	ds_read_b128 v[166:169], v171 offset:8192
	ds_read_b128 v[182:185], v172 offset:8192
	ds_read_b128 v[186:189], v210 offset:8192
	s_waitcnt lgkmcnt(7)
	v_mfma_f32_16x16x32_bf16 v[142:145], v[190:193], v[150:153], v[142:145]
	s_waitcnt lgkmcnt(6)
	v_mfma_f32_16x16x32_bf16 v[142:145], v[194:197], v[154:157], v[142:145]
	s_waitcnt lgkmcnt(5)
	v_mfma_f32_16x16x32_bf16 v[142:145], v[198:201], v[158:161], v[142:145]
	s_waitcnt lgkmcnt(4)
	v_mfma_f32_16x16x32_bf16 v[142:145], v[202:205], v[162:165], v[142:145]
	ds_read_b128 v[190:193], v137 offset:12288
	ds_read_b128 v[194:197], v171 offset:12288
	ds_read_b128 v[198:201], v172 offset:12288
	ds_read_b128 v[202:205], v210 offset:12288
	s_waitcnt lgkmcnt(7)
	v_mfma_f32_16x16x32_bf16 v[32:35], v[138:141], v[150:153], v[34:37]
	s_waitcnt lgkmcnt(6)
	v_mfma_f32_16x16x32_bf16 v[32:35], v[166:169], v[154:157], v[32:35]
	s_waitcnt lgkmcnt(5)
	v_mfma_f32_16x16x32_bf16 v[32:35], v[182:185], v[158:161], v[32:35]
	s_waitcnt lgkmcnt(4)
	v_mfma_f32_16x16x32_bf16 v[32:35], v[186:189], v[162:165], v[32:35]
	ds_read_b128 v[138:141], v137 offset:16384
	ds_read_b128 v[166:169], v171 offset:16384
	ds_read_b128 v[182:185], v172 offset:16384
	ds_read_b128 v[186:189], v210 offset:16384
	s_waitcnt lgkmcnt(7)
	v_mfma_f32_16x16x32_bf16 v[146:149], v[190:193], v[150:153], v[146:149]
	s_waitcnt lgkmcnt(6)
	v_mfma_f32_16x16x32_bf16 v[146:149], v[194:197], v[154:157], v[146:149]
	s_waitcnt lgkmcnt(5)
	v_mfma_f32_16x16x32_bf16 v[146:149], v[198:201], v[158:161], v[146:149]
	s_waitcnt lgkmcnt(4)
	v_mfma_f32_16x16x32_bf16 v[146:149], v[202:205], v[162:165], v[146:149]
	ds_read_b128 v[190:193], v137 offset:20480
	ds_read_b128 v[194:197], v171 offset:20480
	ds_read_b128 v[198:201], v172 offset:20480
	ds_read_b128 v[202:205], v210 offset:20480
	v_xor_b32_e32 v153, 0x80008000, v153
	v_xor_b32_e32 v152, 0x80008000, v152
	v_xor_b32_e32 v151, 0x80008000, v151
	v_xor_b32_e32 v150, 0x80008000, v150
	v_xor_b32_e32 v157, 0x80008000, v157
	v_xor_b32_e32 v156, 0x80008000, v156
	s_waitcnt lgkmcnt(7)
	v_mfma_f32_16x16x32_bf16 v[138:141], v[138:141], v[150:153], 0
	v_xor_b32_e32 v155, 0x80008000, v155
	v_xor_b32_e32 v154, 0x80008000, v154
	v_xor_b32_e32 v161, 0x80008000, v161
	v_xor_b32_e32 v160, 0x80008000, v160
	s_waitcnt lgkmcnt(6)
	v_mfma_f32_16x16x32_bf16 v[138:141], v[166:169], v[154:157], v[138:141]
	v_xor_b32_e32 v159, 0x80008000, v159
	v_xor_b32_e32 v158, 0x80008000, v158
	v_xor_b32_e32 v165, 0x80008000, v165
	v_xor_b32_e32 v164, 0x80008000, v164
	s_waitcnt lgkmcnt(5)
	v_mfma_f32_16x16x32_bf16 v[138:141], v[182:185], v[158:161], v[138:141]
	v_xor_b32_e32 v163, 0x80008000, v163
	v_xor_b32_e32 v162, 0x80008000, v162
	s_waitcnt lgkmcnt(4)
	s_nop 0
	v_mfma_f32_16x16x32_bf16 v[138:141], v[186:189], v[162:165], v[138:141]
	ds_read_b128 v[166:169], v137 offset:24576
	ds_read_b128 v[182:185], v171 offset:24576
	ds_read_b128 v[186:189], v172 offset:24576
	ds_read_b128 v[206:209], v210 offset:24576
	s_waitcnt lgkmcnt(7)
	v_mfma_f32_16x16x32_bf16 v[190:193], v[190:193], v[150:153], 0
	s_waitcnt lgkmcnt(6)
	v_mfma_f32_16x16x32_bf16 v[190:193], v[194:197], v[154:157], v[190:193]
	s_waitcnt lgkmcnt(5)
	v_mfma_f32_16x16x32_bf16 v[190:193], v[198:201], v[158:161], v[190:193]
	s_waitcnt lgkmcnt(4)
	v_mfma_f32_16x16x32_bf16 v[190:193], v[202:205], v[162:165], v[190:193]
	ds_read_b128 v[194:197], v137 offset:28672
	ds_read_b128 v[198:201], v171 offset:28672
	ds_read_b128 v[202:205], v172 offset:28672
	ds_read_b128 v[210:213], v210 offset:28672
	s_waitcnt lgkmcnt(7)
	v_mfma_f32_16x16x32_bf16 v[166:169], v[166:169], v[150:153], 0
	v_and_b32_e32 v36, 0x70, v42
	v_lshl_add_u32 v37, v135, 7, s19
	v_xad_u32 v137, v36, v43, v37
	s_waitcnt lgkmcnt(6)
	v_mfma_f32_16x16x32_bf16 v[166:169], v[182:185], v[154:157], v[166:169]
	v_xad_u32 v170, v170, v36, v37
	ds_read_b128 v[182:185], v137 offset:49152
	s_waitcnt lgkmcnt(6)
	v_mfma_f32_16x16x32_bf16 v[166:169], v[186:189], v[158:161], v[166:169]
	s_waitcnt lgkmcnt(5)
	v_mfma_f32_16x16x32_bf16 v[166:169], v[206:209], v[162:165], v[166:169]
	ds_read_b128 v[186:189], v170 offset:49152
	ds_read_b128 v[206:209], v137 offset:51200
	ds_read_b128 v[230:233], v170 offset:51200
	s_waitcnt lgkmcnt(7)
	v_mfma_f32_16x16x32_bf16 v[150:153], v[194:197], v[150:153], 0
	s_waitcnt lgkmcnt(6)
	v_mfma_f32_16x16x32_bf16 v[150:153], v[198:201], v[154:157], v[150:153]
	s_waitcnt lgkmcnt(5)
	v_mfma_f32_16x16x32_bf16 v[150:153], v[202:205], v[158:161], v[150:153]
	ds_read_b128 v[154:157], v137 offset:53248
	ds_read_b128 v[158:161], v137 offset:55296
	ds_read_b128 v[194:197], v170 offset:53248
	ds_read_b128 v[198:201], v170 offset:55296
	s_waitcnt lgkmcnt(8)
	v_mfma_f32_16x16x32_bf16 v[150:153], v[210:213], v[162:165], v[150:153]
	v_cvt_pk_bf16_f32 v162, v38, v39
	v_cvt_pk_bf16_f32 v163, v40, v41
	v_cvt_pk_bf16_f32 v164, v142, v143
	v_cvt_pk_bf16_f32 v165, v144, v145
	v_cvt_pk_bf16_f32 v142, v32, v33
	v_cvt_pk_bf16_f32 v143, v34, v35
	s_waitcnt lgkmcnt(7)
	v_mfma_f32_16x16x32_bf16 v[36:39], v[182:185], v[162:165], v[138:141]
	v_cvt_pk_bf16_f32 v144, v146, v147
	v_cvt_pk_bf16_f32 v145, v148, v149
	s_waitcnt lgkmcnt(5)
	v_mfma_f32_16x16x32_bf16 v[32:35], v[206:209], v[162:165], v[190:193]
	v_mfma_f32_16x16x32_bf16 v[138:141], v[186:189], v[142:145], v[36:39]
	ds_read_b128 v[146:149], v137 offset:32768
	ds_read_b128 v[182:185], v137 offset:34816
	ds_read_b128 v[186:189], v170 offset:32768
	ds_read_b128 v[190:193], v170 offset:34816
	s_waitcnt lgkmcnt(8)
	v_mfma_f32_16x16x32_bf16 v[40:43], v[230:233], v[142:145], v[32:35]
	s_waitcnt lgkmcnt(7)
	v_mfma_f32_16x16x32_bf16 v[32:35], v[154:157], v[162:165], v[166:169]
	s_waitcnt lgkmcnt(5)
	v_mfma_f32_16x16x32_bf16 v[36:39], v[194:197], v[142:145], v[32:35]
	v_mfma_f32_16x16x32_bf16 v[32:35], v[158:161], v[162:165], v[150:153]
	s_nop 2
	ds_read_b128 v[150:153], v137 offset:36864
	ds_read_b128 v[154:157], v170 offset:36864
	ds_read_b128 v[158:161], v137 offset:38912
	ds_read_b128 v[166:169], v170 offset:38912
	s_waitcnt lgkmcnt(8)
	v_mfma_f32_16x16x32_bf16 v[32:35], v[198:201], v[142:145], v[32:35]
	v_mul_f32_e64 v2, v124, v2
	v_mul_f32_e64 v3, v124, v3
	v_pk_mul_f32 v[0:1], v[124:125], v[0:1] op_sel_hi:[0,1]
	v_pk_mul_f32 v[6:7], v[124:125], v[6:7] op_sel_hi:[0,1]
	v_pk_mul_f32 v[4:5], v[124:125], v[4:5] op_sel_hi:[0,1]
	s_waitcnt lgkmcnt(7)
	v_mfma_f32_16x16x32_bf16 v[0:3], v[146:149], v[162:165], v[0:3]
	s_waitcnt lgkmcnt(6)
	v_mfma_f32_16x16x32_bf16 v[4:7], v[182:185], v[162:165], v[4:7]
	s_waitcnt lgkmcnt(5)
	v_mfma_f32_16x16x32_bf16 v[0:3], v[186:189], v[142:145], v[0:3]
	s_waitcnt lgkmcnt(4)
	v_mfma_f32_16x16x32_bf16 v[4:7], v[190:193], v[142:145], v[4:7]
	ds_read_b128 v[146:149], v137 offset:40960
	ds_read_b128 v[182:185], v170 offset:40960
	ds_read_b128 v[186:189], v137 offset:43008
	ds_read_b128 v[190:193], v170 offset:43008
	v_pk_mul_f32 v[10:11], v[124:125], v[10:11] op_sel_hi:[0,1]
	v_pk_mul_f32 v[8:9], v[124:125], v[8:9] op_sel_hi:[0,1]
	v_pk_mul_f32 v[14:15], v[124:125], v[14:15] op_sel_hi:[0,1]
	v_pk_mul_f32 v[12:13], v[124:125], v[12:13] op_sel_hi:[0,1]
	s_waitcnt lgkmcnt(7)
	v_mfma_f32_16x16x32_bf16 v[8:11], v[150:153], v[162:165], v[8:11]
	s_waitcnt lgkmcnt(5)
	v_mfma_f32_16x16x32_bf16 v[12:15], v[158:161], v[162:165], v[12:15]
	v_mfma_f32_16x16x32_bf16 v[8:11], v[154:157], v[142:145], v[8:11]
	s_waitcnt lgkmcnt(4)
	v_mfma_f32_16x16x32_bf16 v[12:15], v[166:169], v[142:145], v[12:15]
	ds_read_b128 v[150:153], v137 offset:45056
	ds_read_b128 v[154:157], v170 offset:45056
	ds_read_b128 v[158:161], v137 offset:47104
	ds_read_b128 v[166:169], v170 offset:47104
	v_pk_mul_f32 v[18:19], v[124:125], v[18:19] op_sel_hi:[0,1]
	v_pk_mul_f32 v[16:17], v[124:125], v[16:17] op_sel_hi:[0,1]
	v_pk_mul_f32 v[22:23], v[124:125], v[22:23] op_sel_hi:[0,1]
	v_pk_mul_f32 v[20:21], v[124:125], v[20:21] op_sel_hi:[0,1]
	s_waitcnt lgkmcnt(7)
	v_mfma_f32_16x16x32_bf16 v[16:19], v[146:149], v[162:165], v[16:19]
	s_waitcnt lgkmcnt(5)
	v_mfma_f32_16x16x32_bf16 v[20:23], v[186:189], v[162:165], v[20:23]
	v_mfma_f32_16x16x32_bf16 v[16:19], v[182:185], v[142:145], v[16:19]
	s_waitcnt lgkmcnt(4)
	v_mfma_f32_16x16x32_bf16 v[20:23], v[190:193], v[142:145], v[20:23]
	s_ashr_i32 s19, s18, 31
	s_lshl_b64 s[20:21], s[18:19], 11
	v_pk_mul_f32 v[30:31], v[124:125], v[30:31] op_sel_hi:[0,1]
	v_pk_mul_f32 v[28:29], v[124:125], v[28:29] op_sel_hi:[0,1]
	v_pk_mul_f32 v[26:27], v[124:125], v[26:27] op_sel_hi:[0,1]
	v_pk_mul_f32 v[24:25], v[124:125], v[24:25] op_sel_hi:[0,1]
	s_add_u32 s20, s23, s20
	s_addc_u32 s21, s62, s21
	s_waitcnt lgkmcnt(3)
	v_mfma_f32_16x16x32_bf16 v[28:31], v[150:153], v[162:165], v[28:31]
	s_andn2_b64 vcc, exec, s[12:13]
	s_waitcnt lgkmcnt(1)
	v_mfma_f32_16x16x32_bf16 v[24:27], v[158:161], v[162:165], v[24:27]
	v_mfma_f32_16x16x32_bf16 v[28:31], v[154:157], v[142:145], v[28:31]
	s_waitcnt lgkmcnt(0)
	v_mfma_f32_16x16x32_bf16 v[24:27], v[166:169], v[142:145], v[24:27]
	s_cbranch_vccnz .Lscan_smp
	s_bitcmp1_b32 s64, 0
	s_mov_b32 s65, 0x20010
	s_cselect_b32 s65, 0x1c000, s65
	v_lshlrev_b32_e32 v137, 10, v136
	s_lshl_b32 s66, s28, 1
	v_lshl_add_u32 v137, v135, 1, v137
	s_add_i32 s66, s66, s65
	v_lshlrev_b32_e32 v171, 11, v136
	v_add_u32_e32 v137, s66, v137
	v_lshl_add_u32 v171, v135, 4, v171
	v_cvt_pk_bf16_f32 v124, v138, v138
	ds_write_b16 v137, v124
	v_cvt_pk_bf16_f32 v124, v139, v139
	ds_write_b16 v137, v124 offset:256
	v_cvt_pk_bf16_f32 v124, v140, v140
	ds_write_b16 v137, v124 offset:512
	v_cvt_pk_bf16_f32 v124, v141, v141
	ds_write_b16 v137, v124 offset:768
	v_cvt_pk_bf16_f32 v124, v40, v40
	ds_write_b16 v137, v124 offset:4096
	v_cvt_pk_bf16_f32 v124, v41, v41
	ds_write_b16 v137, v124 offset:4352
	v_cvt_pk_bf16_f32 v124, v42, v42
	ds_write_b16 v137, v124 offset:4608
	v_cvt_pk_bf16_f32 v124, v43, v43
	ds_write_b16 v137, v124 offset:4864
	v_cvt_pk_bf16_f32 v124, v36, v36
	ds_write_b16 v137, v124 offset:8192
	v_cvt_pk_bf16_f32 v124, v37, v37
	ds_write_b16 v137, v124 offset:8448
	v_cvt_pk_bf16_f32 v124, v38, v38
	ds_write_b16 v137, v124 offset:8704
	v_cvt_pk_bf16_f32 v124, v39, v39
	ds_write_b16 v137, v124 offset:8960
	v_cvt_pk_bf16_f32 v124, v32, v32
	ds_write_b16 v137, v124 offset:12288
	v_cvt_pk_bf16_f32 v124, v33, v33
	ds_write_b16 v137, v124 offset:12544
	v_cvt_pk_bf16_f32 v124, v34, v34
	ds_write_b16 v137, v124 offset:12800
	v_cvt_pk_bf16_f32 v124, v35, v35
	ds_write_b16 v137, v124 offset:13056
	s_lshl_b32 s66, s28, 6
	s_add_i32 s66, s66, s65
	v_lshl_add_u32 v170, v125, 4, s66
	s_lshl_b32 s66, s28, 9
	v_add_u32_e32 v171, s66, v171
	s_add_u32 s58, s20, 0x10000
	s_addc_u32 s59, s21, 0
	s_add_i32 s18, s18, 64
	s_waitcnt vmcnt(0) lgkmcnt(0)
	s_barrier
	ds_read_b128 v[146:149], v170
	ds_read_b128 v[150:153], v170 offset:8192
	v_mov_b64_e32 v[34:35], v[126:127]
	v_mov_b64_e32 v[38:39], v[128:129]
	v_mov_b64_e32 v[36:37], v[130:131]
	v_mov_b64_e32 v[32:33], v[132:133]
	v_mov_b32_e32 v124, v134
	s_cmp_eq_u32 s22, s64
	s_mov_b32 s19, s64
	s_waitcnt lgkmcnt(1)
	global_store_dwordx4 v171, v[146:149], s[20:21]
	s_waitcnt lgkmcnt(0)
	global_store_dwordx4 v171, v[150:153], s[58:59]
	s_cbranch_scc1 .LBB0_1083
	s_branch .LBB0_1090
.Lscan_smp:
	v_lshl_add_u32 v124, v136, 12, s28
	v_or_b32_e32 v172, v124, v135
	v_cvt_pk_bf16_f32 v124, v138, s0
	v_lshl_add_u64 v[136:137], v[172:173], 1, s[20:21]
	global_store_short v[136:137], v124, off
	v_add_u32_e32 v136, 0x400, v172
	v_mov_b32_e32 v137, v173
	v_cvt_pk_bf16_f32 v124, v139, s0
	v_lshl_add_u64 v[136:137], v[136:137], 1, s[20:21]
	global_store_short v[136:137], v124, off
	v_add_u32_e32 v136, 0x800, v172
	v_mov_b32_e32 v137, v173
	v_cvt_pk_bf16_f32 v124, v140, s0
	v_lshl_add_u64 v[136:137], v[136:137], 1, s[20:21]
	global_store_short v[136:137], v124, off
	v_add_u32_e32 v136, 0xc00, v172
	v_mov_b32_e32 v137, v173
	v_cvt_pk_bf16_f32 v124, v141, s0
	v_lshl_add_u64 v[136:137], v[136:137], 1, s[20:21]
	global_store_short v[136:137], v124, off
	s_branch .LBB0_1089

.LBB0_1101:
	s_or_b64 exec, exec, s[6:7]
	s_branch .LBB0_1102
.Lcc_spread:
	s_cmp_gt_i32 s2, 31
	s_cselect_b64 s[16:17], -1, 0
	s_branch .LBB0_1103

	.amdhsa_kernel _Z14fwd_megakernel6Params
		.amdhsa_group_segment_fixed_size 16384
		.amdhsa_private_segment_fixed_size 0
		.amdhsa_kernarg_size 472
		.amdhsa_user_sgpr_count 2
		.amdhsa_user_sgpr_dispatch_ptr 0
		.amdhsa_user_sgpr_queue_ptr 0
		.amdhsa_user_sgpr_kernarg_segment_ptr 1
		.amdhsa_user_sgpr_dispatch_id 0
		.amdhsa_user_sgpr_kernarg_preload_length 0
		.amdhsa_user_sgpr_kernarg_preload_offset 0
		.amdhsa_user_sgpr_private_segment_size 0
		.amdhsa_uses_dynamic_stack 0
		.amdhsa_enable_private_segment 0
		.amdhsa_system_sgpr_workgroup_id_x 1
		.amdhsa_system_sgpr_workgroup_id_y 0
		.amdhsa_system_sgpr_workgroup_id_z 0
		.amdhsa_system_sgpr_workgroup_info 0
		.amdhsa_system_vgpr_workitem_id 2
		.amdhsa_next_free_vgpr 256
		.amdhsa_next_free_sgpr 102
		.amdhsa_accum_offset 256
		.amdhsa_reserve_vcc 1
		.amdhsa_float_round_mode_32 0
		.amdhsa_float_round_mode_16_64 0
		.amdhsa_float_denorm_mode_32 3
		.amdhsa_float_denorm_mode_16_64 3
		.amdhsa_dx10_clamp 1
		.amdhsa_ieee_mode 1
		.amdhsa_fp16_overflow 0
		.amdhsa_tg_split 0
		.amdhsa_exception_fp_ieee_invalid_op 0
		.amdhsa_exception_fp_denorm_src 0
		.amdhsa_exception_fp_ieee_div_zero 0
		.amdhsa_exception_fp_ieee_overflow 0
		.amdhsa_exception_fp_ieee_underflow 0
		.amdhsa_exception_fp_ieee_inexact 0
		.amdhsa_exception_int_div_zero 0
	.end_amdhsa_kernel

amdhsa.kernels:
  - .agpr_count:     0
    .args:
      - .offset:         0
        .size:           216
        .value_kind:     by_value
      - .offset:         216
        .size:           4
        .value_kind:     hidden_block_count_x
      - .offset:         220
        .size:           4
        .value_kind:     hidden_block_count_y
      - .offset:         224
        .size:           4
        .value_kind:     hidden_block_count_z
      - .offset:         228
        .size:           2
        .value_kind:     hidden_group_size_x
      - .offset:         230
        .size:           2
        .value_kind:     hidden_group_size_y
      - .offset:         232
        .size:           2
        .value_kind:     hidden_group_size_z
      - .offset:         234
        .size:           2
        .value_kind:     hidden_remainder_x
      - .offset:         236
        .size:           2
        .value_kind:     hidden_remainder_y
      - .offset:         238
        .size:           2
        .value_kind:     hidden_remainder_z
      - .offset:         256
        .size:           8
        .value_kind:     hidden_global_offset_x
      - .offset:         264
        .size:           8
        .value_kind:     hidden_global_offset_y
      - .offset:         272
        .size:           8
        .value_kind:     hidden_global_offset_z
      - .offset:         280
        .size:           2
        .value_kind:     hidden_grid_dims
      - .offset:         304
        .size:           8
        .value_kind:     hidden_multigrid_sync_arg
      - .offset:         336
        .size:           4
        .value_kind:     hidden_dynamic_lds_size
    .group_segment_fixed_size: 16384
    .kernarg_segment_align: 8
    .kernarg_segment_size: 472
    .language:       OpenCL C
    .language_version:
      - 2
      - 0
    .max_flat_workgroup_size: 512
    .name:           _Z14fwd_megakernel6Params
    .private_segment_fixed_size: 0
    .sgpr_count:     108
    .sgpr_spill_count: 83
    .symbol:         _Z14fwd_megakernel6Params.kd
    .uniform_work_group_size: 1
    .uses_dynamic_stack: false
    .vgpr_count:     256
    .vgpr_spill_count: 0
    .wavefront_size: 64
